# top-k tile start: LDS histogram/bitmap cleared by 11 straight-line ds_write_b128 instead of two exec-mask loops
# baseline (speedup 1.0000x reference)
.LBB0_302:
	s_nop 0
	v_readlane_b32 s2, v252, 27
	v_readlane_b32 s3, v252, 52
	s_mul_i32 s2, s3, s2
	v_readlane_b32 s3, v252, 53
	s_add_i32 s6, s3, s2
	s_cmpk_gt_i32 s6, 0x803
	s_mov_b64 s[2:3], -1
	s_cbranch_scc1 .LBB0_297
	s_barrier
	v_lshlrev_b32_e32 v0, 2, v159
	v_mov_b32_e32 v246, 0
	v_mov_b32_e32 v247, 0
	v_mov_b32_e32 v248, 0
	v_mov_b32_e32 v249, 0
	ds_write_b128 v0, v[246:249]
	ds_write_b128 v0, v[246:249] offset:4096
	ds_write_b128 v0, v[246:249] offset:8192
	ds_write_b128 v0, v[246:249] offset:12288
	ds_write_b128 v0, v[246:249] offset:16384
	ds_write_b128 v0, v[246:249] offset:20480
	ds_write_b128 v0, v[246:249] offset:24576
	ds_write_b128 v0, v[246:249] offset:28672
	ds_write_b128 v0, v[246:249] offset:49152
	ds_write_b128 v0, v[246:249] offset:53248
	ds_write_b128 v0, v[246:249] offset:57344
	s_mov_b64 s[2:3], exec
	v_readlane_b32 s4, v252, 32
	v_readlane_b32 s5, v252, 33
	s_and_b64 s[4:5], s[2:3], s[4:5]
	s_mov_b64 exec, s[4:5]
	ds_write_b32 v159, v177 offset:57600
	s_or_b64 exec, exec, s[2:3]
	s_lshl_b32 s2, s6, 2
	s_and_b32 s10, s2, -8
	s_sub_i32 s7, 0x2008, s10
	s_bitcmp1_b32 s6, 0
	s_cselect_b32 s5, 0x2010, 0
	s_add_i32 s4, s7, s5
	v_or_b32_e32 v176, s4, v158
	v_lshlrev_b64 v[0:1], 10, v[176:177]
	v_lshl_add_u64 v[0:1], v[134:135], 0, v[0:1]
	global_load_dwordx4 v[32:35], v[0:1], off
	global_load_dwordx4 v[36:39], v[0:1], off offset:32
	global_load_dwordx4 v[40:43], v[0:1], off offset:64
	global_load_dwordx4 v[44:47], v[0:1], off offset:96
	v_or_b32_e32 v0, s4, v161
	v_mov_b32_e32 v1, v177
	v_readlane_b32 s2, v252, 24
	v_lshlrev_b64 v[0:1], 5, v[0:1]
	v_readlane_b32 s3, v252, 25
	v_or_b32_e32 v176, 4, v176
	v_writelane_b32 v252, s4, 54
	v_lshl_add_u64 v[0:1], s[2:3], 0, v[0:1]
	global_load_dwordx4 v[48:51], v[0:1], off
	global_load_dwordx4 v[52:55], v[0:1], off offset:16
	global_load_dwordx4 v[56:59], v[0:1], off offset:32
	global_load_dwordx4 v[60:63], v[0:1], off offset:48
	v_lshlrev_b64 v[0:1], 10, v[176:177]
	v_lshl_add_u64 v[0:1], v[134:135], 0, v[0:1]
	v_or_b32_e32 v176, s4, v168
	global_load_dwordx4 v[64:67], v[0:1], off
	global_load_dwordx4 v[68:71], v[0:1], off offset:32
	global_load_dwordx4 v[72:75], v[0:1], off offset:64
	global_load_dwordx4 v[76:79], v[0:1], off offset:96
	v_lshlrev_b64 v[0:1], 5, v[176:177]
	v_lshl_add_u64 v[0:1], s[2:3], 0, v[0:1]
	global_load_dwordx4 v[80:83], v[0:1], off
	global_load_dwordx4 v[84:87], v[0:1], off offset:16
	global_load_dwordx4 v[88:91], v[0:1], off offset:32
	global_load_dwordx4 v[92:95], v[0:1], off offset:48
	s_lshr_b32 s2, s5, 9
	s_add_i32 s2, s2, s5
	v_mov_b32_e32 v0, s2
	s_lshr_b32 s18, s7, 5
	s_add_i32 s2, s10, 0xffffdfef
	v_lshlrev_b32_e32 v176, 7, v0
	s_cmpk_gt_i32 s2, 0xfbfe
	v_or_b32_e32 v238, s7, v161
	v_or_b32_e32 v239, s7, v167
	v_or_b32_e32 v240, s7, v168
	v_writelane_b32 v252, s7, 55
	v_or_b32_e32 v241, s7, v169
	v_lshl_add_u64 v[154:155], v[136:137], 0, v[176:177]
	v_writelane_b32 v252, s5, 56
	s_waitcnt lgkmcnt(0)
	s_barrier
	s_cbranch_scc1 .LBB0_343
	v_cmp_ge_i32_e32 vcc, s18, v138
	s_and_saveexec_b64 s[2:3], vcc
	s_cbranch_execz .LBB0_331
	v_lshl_add_u64 v[0:1], v[154:155], 0, v[142:143]
	global_load_dwordx4 v[96:99], v[0:1], off offset:3072
	global_load_dwordx4 v[100:103], v[0:1], off offset:2048
	global_load_dwordx4 v[104:107], v[0:1], off offset:1024
	global_load_dwordx4 v[108:111], v[0:1], off
	s_mov_b64 s[8:9], 0
	v_mov_b32_e32 v116, v231
	v_mov_b32_e32 v117, v138
	s_branch .LBB0_315
